# GEMM K-loop heads aligned to 64 bytes (p2align before the four loop labels); on top of no-setprio + all-to-all release
# baseline (speedup 1.0000x reference)
.LBB0_294:
	s_ashr_i32 s17, s16, 31
	s_lshl_b64 s[4:5], s[16:17], 20
	s_add_u32 s18, s74, s4
	s_addc_u32 s19, s75, s5
	s_and_b64 s[4:5], s[36:37], exec
	s_cselect_b32 s17, s19, s1
	s_cselect_b32 s25, s18, s0
	s_ashr_i32 s15, s14, 31
	s_lshl_b64 s[4:5], s[14:15], 20
	s_add_u32 s20, s22, s4
	s_addc_u32 s21, s23, s5
	s_and_b64 s[4:5], s[36:37], exec
	s_cselect_b32 s15, s21, s3
	s_cselect_b32 s28, s20, s2
	s_add_u32 s0, s0, 0x80080
	s_addc_u32 s1, s1, 0
	s_add_u32 s51, s2, 0x100
	v_mov_b32_e32 v2, 0
	s_addc_u32 s52, s3, 0
	s_mov_b32 s53, -2
	v_mov_b32_e32 v3, v2
	v_mov_b32_e32 v4, v2
	v_mov_b32_e32 v5, v2
	v_mov_b32_e32 v6, v2
	v_mov_b32_e32 v7, v2
	v_mov_b32_e32 v8, v2
	v_mov_b32_e32 v9, v2
	v_mov_b32_e32 v10, v2
	v_mov_b32_e32 v11, v2
	v_mov_b32_e32 v12, v2
	v_mov_b32_e32 v13, v2
	v_mov_b32_e32 v14, v2
	v_mov_b32_e32 v15, v2
	v_mov_b32_e32 v16, v2
	v_mov_b32_e32 v17, v2
	v_mov_b32_e32 v18, v2
	v_mov_b32_e32 v19, v2
	v_mov_b32_e32 v20, v2
	v_mov_b32_e32 v21, v2
	v_mov_b32_e32 v26, v2
	v_mov_b32_e32 v27, v2
	v_mov_b32_e32 v28, v2
	v_mov_b32_e32 v29, v2
	v_mov_b32_e32 v34, v2
	v_mov_b32_e32 v35, v2
	v_mov_b32_e32 v36, v2
	v_mov_b32_e32 v37, v2
	v_mov_b32_e32 v42, v2
	v_mov_b32_e32 v43, v2
	v_mov_b32_e32 v44, v2
	v_mov_b32_e32 v45, v2
	v_mov_b32_e32 v22, v2
	v_mov_b32_e32 v23, v2
	v_mov_b32_e32 v24, v2
	v_mov_b32_e32 v25, v2
	v_mov_b32_e32 v30, v2
	v_mov_b32_e32 v31, v2
	v_mov_b32_e32 v32, v2
	v_mov_b32_e32 v33, v2
	v_mov_b32_e32 v38, v2
	v_mov_b32_e32 v39, v2
	v_mov_b32_e32 v40, v2
	v_mov_b32_e32 v41, v2
	v_mov_b32_e32 v46, v2
	v_mov_b32_e32 v47, v2
	v_mov_b32_e32 v48, v2
	v_mov_b32_e32 v49, v2
	v_mov_b32_e32 v50, v2
	v_mov_b32_e32 v51, v2
	v_mov_b32_e32 v52, v2
	v_mov_b32_e32 v53, v2
	v_mov_b32_e32 v54, v2
	v_mov_b32_e32 v55, v2
	v_mov_b32_e32 v56, v2
	v_mov_b32_e32 v57, v2
	v_mov_b32_e32 v58, v2
	v_mov_b32_e32 v59, v2
	v_mov_b32_e32 v60, v2
	v_mov_b32_e32 v61, v2
	v_mov_b32_e32 v62, v2
	v_mov_b32_e32 v63, v2
	v_mov_b32_e32 v64, v2
	v_mov_b32_e32 v65, v2
	v_mov_b32_e32 v68, v2
	v_mov_b32_e32 v69, v2
	v_mov_b32_e32 v70, v2
	v_mov_b32_e32 v71, v2
	v_mov_b32_e32 v72, v2
	v_mov_b32_e32 v73, v2
	v_mov_b32_e32 v74, v2
	v_mov_b32_e32 v75, v2
	v_mov_b32_e32 v76, v2
	v_mov_b32_e32 v77, v2
	v_mov_b32_e32 v78, v2
	v_mov_b32_e32 v79, v2
	v_mov_b32_e32 v80, v2
	v_mov_b32_e32 v81, v2
	v_mov_b32_e32 v82, v2
	v_mov_b32_e32 v83, v2
	v_mov_b32_e32 v84, v2
	v_mov_b32_e32 v85, v2
	v_mov_b32_e32 v86, v2
	v_mov_b32_e32 v87, v2
	v_mov_b32_e32 v92, v2
	v_mov_b32_e32 v93, v2
	v_mov_b32_e32 v94, v2
	v_mov_b32_e32 v95, v2
	v_mov_b32_e32 v100, v2
	v_mov_b32_e32 v101, v2
	v_mov_b32_e32 v102, v2
	v_mov_b32_e32 v103, v2
	v_mov_b32_e32 v108, v2
	v_mov_b32_e32 v109, v2
	v_mov_b32_e32 v110, v2
	v_mov_b32_e32 v111, v2
	v_mov_b32_e32 v88, v2
	v_mov_b32_e32 v89, v2
	v_mov_b32_e32 v90, v2
	v_mov_b32_e32 v91, v2
	v_mov_b32_e32 v96, v2
	v_mov_b32_e32 v97, v2
	v_mov_b32_e32 v98, v2
	v_mov_b32_e32 v99, v2
	v_mov_b32_e32 v104, v2
	v_mov_b32_e32 v105, v2
	v_mov_b32_e32 v106, v2
	v_mov_b32_e32 v107, v2
	v_mov_b32_e32 v112, v2
	v_mov_b32_e32 v113, v2
	v_mov_b32_e32 v114, v2
	v_mov_b32_e32 v115, v2
	v_mov_b32_e32 v116, v2
	v_mov_b32_e32 v117, v2
	v_mov_b32_e32 v118, v2
	v_mov_b32_e32 v119, v2
	v_mov_b32_e32 v120, v2
	v_mov_b32_e32 v121, v2
	v_mov_b32_e32 v122, v2
	v_mov_b32_e32 v123, v2
	v_mov_b32_e32 v124, v2
	v_mov_b32_e32 v125, v2
	v_mov_b32_e32 v126, v2
	v_mov_b32_e32 v127, v2
	v_mov_b32_e32 v128, v2
	v_mov_b32_e32 v129, v2
	v_mov_b32_e32 v130, v2
	v_mov_b32_e32 v131, v2
	s_mov_b64 s[58:59], 0x80
	.p2align 6

.LBB0_1490:
	s_ashr_i32 s13, s12, 31
	s_lshl_b64 s[14:15], s[12:13], 20
	s_add_u32 s14, s26, s14
	s_addc_u32 s15, s27, s15
	s_and_b64 s[16:17], s[0:1], exec
	s_cselect_b32 s13, s15, s19
	s_cselect_b32 s50, s14, s18
	s_ashr_i32 s11, s10, 31
	s_lshl_b64 s[16:17], s[10:11], 20
	s_add_u32 s16, s28, s16
	s_addc_u32 s17, s40, s17
	s_and_b64 s[22:23], s[0:1], exec
	s_cselect_b32 s11, s17, s21
	s_cselect_b32 s51, s16, s20
	s_add_u32 s52, s20, 0x100
	v_mov_b32_e32 v2, 0
	s_addc_u32 s53, s21, 0
	s_mov_b32 s54, -2
	v_mov_b32_e32 v3, v2
	v_mov_b32_e32 v4, v2
	v_mov_b32_e32 v5, v2
	v_mov_b32_e32 v6, v2
	v_mov_b32_e32 v7, v2
	v_mov_b32_e32 v8, v2
	v_mov_b32_e32 v9, v2
	v_mov_b32_e32 v10, v2
	v_mov_b32_e32 v11, v2
	v_mov_b32_e32 v12, v2
	v_mov_b32_e32 v13, v2
	v_mov_b32_e32 v18, v2
	v_mov_b32_e32 v19, v2
	v_mov_b32_e32 v20, v2
	v_mov_b32_e32 v21, v2
	v_mov_b32_e32 v26, v2
	v_mov_b32_e32 v27, v2
	v_mov_b32_e32 v28, v2
	v_mov_b32_e32 v29, v2
	v_mov_b32_e32 v30, v2
	v_mov_b32_e32 v31, v2
	v_mov_b32_e32 v32, v2
	v_mov_b32_e32 v33, v2
	v_mov_b32_e32 v38, v2
	v_mov_b32_e32 v39, v2
	v_mov_b32_e32 v40, v2
	v_mov_b32_e32 v41, v2
	v_mov_b32_e32 v42, v2
	v_mov_b32_e32 v43, v2
	v_mov_b32_e32 v44, v2
	v_mov_b32_e32 v45, v2
	v_mov_b32_e32 v14, v2
	v_mov_b32_e32 v15, v2
	v_mov_b32_e32 v16, v2
	v_mov_b32_e32 v17, v2
	v_mov_b32_e32 v22, v2
	v_mov_b32_e32 v23, v2
	v_mov_b32_e32 v24, v2
	v_mov_b32_e32 v25, v2
	v_mov_b32_e32 v34, v2
	v_mov_b32_e32 v35, v2
	v_mov_b32_e32 v36, v2
	v_mov_b32_e32 v37, v2
	v_mov_b32_e32 v46, v2
	v_mov_b32_e32 v47, v2
	v_mov_b32_e32 v48, v2
	v_mov_b32_e32 v49, v2
	v_mov_b32_e32 v50, v2
	v_mov_b32_e32 v51, v2
	v_mov_b32_e32 v52, v2
	v_mov_b32_e32 v53, v2
	v_mov_b32_e32 v54, v2
	v_mov_b32_e32 v55, v2
	v_mov_b32_e32 v56, v2
	v_mov_b32_e32 v57, v2
	v_mov_b32_e32 v58, v2
	v_mov_b32_e32 v59, v2
	v_mov_b32_e32 v60, v2
	v_mov_b32_e32 v61, v2
	v_mov_b32_e32 v62, v2
	v_mov_b32_e32 v63, v2
	v_mov_b32_e32 v64, v2
	v_mov_b32_e32 v65, v2
	v_mov_b32_e32 v68, v2
	v_mov_b32_e32 v69, v2
	v_mov_b32_e32 v70, v2
	v_mov_b32_e32 v71, v2
	v_mov_b32_e32 v72, v2
	v_mov_b32_e32 v73, v2
	v_mov_b32_e32 v74, v2
	v_mov_b32_e32 v75, v2
	v_mov_b32_e32 v80, v2
	v_mov_b32_e32 v81, v2
	v_mov_b32_e32 v82, v2
	v_mov_b32_e32 v83, v2
	v_mov_b32_e32 v88, v2
	v_mov_b32_e32 v89, v2
	v_mov_b32_e32 v90, v2
	v_mov_b32_e32 v91, v2
	v_mov_b32_e32 v92, v2
	v_mov_b32_e32 v93, v2
	v_mov_b32_e32 v94, v2
	v_mov_b32_e32 v95, v2
	v_mov_b32_e32 v96, v2
	v_mov_b32_e32 v97, v2
	v_mov_b32_e32 v98, v2
	v_mov_b32_e32 v99, v2
	v_mov_b32_e32 v104, v2
	v_mov_b32_e32 v105, v2
	v_mov_b32_e32 v106, v2
	v_mov_b32_e32 v107, v2
	v_mov_b32_e32 v108, v2
	v_mov_b32_e32 v109, v2
	v_mov_b32_e32 v110, v2
	v_mov_b32_e32 v111, v2
	v_mov_b32_e32 v76, v2
	v_mov_b32_e32 v77, v2
	v_mov_b32_e32 v78, v2
	v_mov_b32_e32 v79, v2
	v_mov_b32_e32 v84, v2
	v_mov_b32_e32 v85, v2
	v_mov_b32_e32 v86, v2
	v_mov_b32_e32 v87, v2
	v_mov_b32_e32 v100, v2
	v_mov_b32_e32 v101, v2
	v_mov_b32_e32 v102, v2
	v_mov_b32_e32 v103, v2
	v_mov_b32_e32 v112, v2
	v_mov_b32_e32 v113, v2
	v_mov_b32_e32 v114, v2
	v_mov_b32_e32 v115, v2
	v_mov_b32_e32 v116, v2
	v_mov_b32_e32 v117, v2
	v_mov_b32_e32 v118, v2
	v_mov_b32_e32 v119, v2
	v_mov_b32_e32 v120, v2
	v_mov_b32_e32 v121, v2
	v_mov_b32_e32 v122, v2
	v_mov_b32_e32 v123, v2
	v_mov_b32_e32 v124, v2
	v_mov_b32_e32 v125, v2
	v_mov_b32_e32 v126, v2
	v_mov_b32_e32 v127, v2
	v_mov_b32_e32 v128, v2
	v_mov_b32_e32 v129, v2
	v_mov_b32_e32 v130, v2
	v_mov_b32_e32 v131, v2
	s_mov_b64 s[58:59], 0x80
	.p2align 6

.LBB0_1622:
	s_ashr_i32 s7, s6, 31
	s_lshl_b64 s[8:9], s[6:7], 20
	s_add_u32 s8, s74, s8
	s_addc_u32 s9, s75, s9
	s_and_b64 s[10:11], s[38:39], exec
	s_cselect_b32 s7, s9, s13
	s_cselect_b32 s44, s8, s12
	s_ashr_i32 s5, s4, 31
	s_lshl_b64 s[10:11], s[4:5], 20
	s_add_u32 s10, s18, s10
	s_addc_u32 s11, s19, s11
	s_and_b64 s[16:17], s[38:39], exec
	s_cselect_b32 s5, s11, s15
	s_cselect_b32 s45, s10, s14
	s_add_u32 s12, s12, 0x80080
	s_addc_u32 s13, s13, 0
	s_add_u32 s46, s14, 0x100
	v_mov_b32_e32 v2, 0
	s_addc_u32 s47, s15, 0
	s_mov_b32 s48, -2
	v_mov_b32_e32 v3, v2
	v_mov_b32_e32 v4, v2
	v_mov_b32_e32 v5, v2
	v_mov_b32_e32 v10, v2
	v_mov_b32_e32 v11, v2
	v_mov_b32_e32 v12, v2
	v_mov_b32_e32 v13, v2
	v_mov_b32_e32 v18, v2
	v_mov_b32_e32 v19, v2
	v_mov_b32_e32 v20, v2
	v_mov_b32_e32 v21, v2
	v_mov_b32_e32 v26, v2
	v_mov_b32_e32 v27, v2
	v_mov_b32_e32 v28, v2
	v_mov_b32_e32 v29, v2
	v_mov_b32_e32 v34, v2
	v_mov_b32_e32 v35, v2
	v_mov_b32_e32 v36, v2
	v_mov_b32_e32 v37, v2
	v_mov_b32_e32 v42, v2
	v_mov_b32_e32 v43, v2
	v_mov_b32_e32 v44, v2
	v_mov_b32_e32 v45, v2
	v_mov_b32_e32 v50, v2
	v_mov_b32_e32 v51, v2
	v_mov_b32_e32 v52, v2
	v_mov_b32_e32 v53, v2
	v_mov_b32_e32 v58, v2
	v_mov_b32_e32 v59, v2
	v_mov_b32_e32 v60, v2
	v_mov_b32_e32 v61, v2
	v_mov_b32_e32 v6, v2
	v_mov_b32_e32 v7, v2
	v_mov_b32_e32 v8, v2
	v_mov_b32_e32 v9, v2
	v_mov_b32_e32 v14, v2
	v_mov_b32_e32 v15, v2
	v_mov_b32_e32 v16, v2
	v_mov_b32_e32 v17, v2
	v_mov_b32_e32 v22, v2
	v_mov_b32_e32 v23, v2
	v_mov_b32_e32 v24, v2
	v_mov_b32_e32 v25, v2
	v_mov_b32_e32 v30, v2
	v_mov_b32_e32 v31, v2
	v_mov_b32_e32 v32, v2
	v_mov_b32_e32 v33, v2
	v_mov_b32_e32 v38, v2
	v_mov_b32_e32 v39, v2
	v_mov_b32_e32 v40, v2
	v_mov_b32_e32 v41, v2
	v_mov_b32_e32 v46, v2
	v_mov_b32_e32 v47, v2
	v_mov_b32_e32 v48, v2
	v_mov_b32_e32 v49, v2
	v_mov_b32_e32 v54, v2
	v_mov_b32_e32 v55, v2
	v_mov_b32_e32 v56, v2
	v_mov_b32_e32 v57, v2
	v_mov_b32_e32 v62, v2
	v_mov_b32_e32 v63, v2
	v_mov_b32_e32 v64, v2
	v_mov_b32_e32 v65, v2
	v_mov_b32_e32 v68, v2
	v_mov_b32_e32 v69, v2
	v_mov_b32_e32 v70, v2
	v_mov_b32_e32 v71, v2
	v_mov_b32_e32 v76, v2
	v_mov_b32_e32 v77, v2
	v_mov_b32_e32 v78, v2
	v_mov_b32_e32 v79, v2
	v_mov_b32_e32 v84, v2
	v_mov_b32_e32 v85, v2
	v_mov_b32_e32 v86, v2
	v_mov_b32_e32 v87, v2
	v_mov_b32_e32 v92, v2
	v_mov_b32_e32 v93, v2
	v_mov_b32_e32 v94, v2
	v_mov_b32_e32 v95, v2
	v_mov_b32_e32 v100, v2
	v_mov_b32_e32 v101, v2
	v_mov_b32_e32 v102, v2
	v_mov_b32_e32 v103, v2
	v_mov_b32_e32 v108, v2
	v_mov_b32_e32 v109, v2
	v_mov_b32_e32 v110, v2
	v_mov_b32_e32 v111, v2
	v_mov_b32_e32 v116, v2
	v_mov_b32_e32 v117, v2
	v_mov_b32_e32 v118, v2
	v_mov_b32_e32 v119, v2
	v_mov_b32_e32 v124, v2
	v_mov_b32_e32 v125, v2
	v_mov_b32_e32 v126, v2
	v_mov_b32_e32 v127, v2
	v_mov_b32_e32 v72, v2
	v_mov_b32_e32 v73, v2
	v_mov_b32_e32 v74, v2
	v_mov_b32_e32 v75, v2
	v_mov_b32_e32 v80, v2
	v_mov_b32_e32 v81, v2
	v_mov_b32_e32 v82, v2
	v_mov_b32_e32 v83, v2
	v_mov_b32_e32 v88, v2
	v_mov_b32_e32 v89, v2
	v_mov_b32_e32 v90, v2
	v_mov_b32_e32 v91, v2
	v_mov_b32_e32 v96, v2
	v_mov_b32_e32 v97, v2
	v_mov_b32_e32 v98, v2
	v_mov_b32_e32 v99, v2
	v_mov_b32_e32 v104, v2
	v_mov_b32_e32 v105, v2
	v_mov_b32_e32 v106, v2
	v_mov_b32_e32 v107, v2
	v_mov_b32_e32 v112, v2
	v_mov_b32_e32 v113, v2
	v_mov_b32_e32 v114, v2
	v_mov_b32_e32 v115, v2
	v_mov_b32_e32 v120, v2
	v_mov_b32_e32 v121, v2
	v_mov_b32_e32 v122, v2
	v_mov_b32_e32 v123, v2
	v_mov_b32_e32 v128, v2
	v_mov_b32_e32 v129, v2
	v_mov_b32_e32 v130, v2
	v_mov_b32_e32 v131, v2
	s_mov_b64 s[54:55], 0x80
	.p2align 6

.LBB0_1763:
	s_add_u32 s50, s20, 0x100
	v_mov_b32_e32 v2, 0
	s_addc_u32 s51, s21, 0
	s_mov_b32 s52, -2
	v_mov_b32_e32 v3, v2
	v_mov_b32_e32 v4, v2
	v_mov_b32_e32 v5, v2
	v_mov_b32_e32 v6, v2
	v_mov_b32_e32 v7, v2
	v_mov_b32_e32 v8, v2
	v_mov_b32_e32 v9, v2
	v_mov_b32_e32 v10, v2
	v_mov_b32_e32 v11, v2
	v_mov_b32_e32 v12, v2
	v_mov_b32_e32 v13, v2
	v_mov_b32_e32 v18, v2
	v_mov_b32_e32 v19, v2
	v_mov_b32_e32 v20, v2
	v_mov_b32_e32 v21, v2
	v_mov_b32_e32 v26, v2
	v_mov_b32_e32 v27, v2
	v_mov_b32_e32 v28, v2
	v_mov_b32_e32 v29, v2
	v_mov_b32_e32 v30, v2
	v_mov_b32_e32 v31, v2
	v_mov_b32_e32 v32, v2
	v_mov_b32_e32 v33, v2
	v_mov_b32_e32 v38, v2
	v_mov_b32_e32 v39, v2
	v_mov_b32_e32 v40, v2
	v_mov_b32_e32 v41, v2
	v_mov_b32_e32 v42, v2
	v_mov_b32_e32 v43, v2
	v_mov_b32_e32 v44, v2
	v_mov_b32_e32 v45, v2
	v_mov_b32_e32 v14, v2
	v_mov_b32_e32 v15, v2
	v_mov_b32_e32 v16, v2
	v_mov_b32_e32 v17, v2
	v_mov_b32_e32 v22, v2
	v_mov_b32_e32 v23, v2
	v_mov_b32_e32 v24, v2
	v_mov_b32_e32 v25, v2
	v_mov_b32_e32 v34, v2
	v_mov_b32_e32 v35, v2
	v_mov_b32_e32 v36, v2
	v_mov_b32_e32 v37, v2
	v_mov_b32_e32 v46, v2
	v_mov_b32_e32 v47, v2
	v_mov_b32_e32 v48, v2
	v_mov_b32_e32 v49, v2
	v_mov_b32_e32 v50, v2
	v_mov_b32_e32 v51, v2
	v_mov_b32_e32 v52, v2
	v_mov_b32_e32 v53, v2
	v_mov_b32_e32 v54, v2
	v_mov_b32_e32 v55, v2
	v_mov_b32_e32 v56, v2
	v_mov_b32_e32 v57, v2
	v_mov_b32_e32 v58, v2
	v_mov_b32_e32 v59, v2
	v_mov_b32_e32 v60, v2
	v_mov_b32_e32 v61, v2
	v_mov_b32_e32 v62, v2
	v_mov_b32_e32 v63, v2
	v_mov_b32_e32 v64, v2
	v_mov_b32_e32 v65, v2
	v_mov_b32_e32 v68, v2
	v_mov_b32_e32 v69, v2
	v_mov_b32_e32 v70, v2
	v_mov_b32_e32 v71, v2
	v_mov_b32_e32 v72, v2
	v_mov_b32_e32 v73, v2
	v_mov_b32_e32 v74, v2
	v_mov_b32_e32 v75, v2
	v_mov_b32_e32 v80, v2
	v_mov_b32_e32 v81, v2
	v_mov_b32_e32 v82, v2
	v_mov_b32_e32 v83, v2
	v_mov_b32_e32 v88, v2
	v_mov_b32_e32 v89, v2
	v_mov_b32_e32 v90, v2
	v_mov_b32_e32 v91, v2
	v_mov_b32_e32 v92, v2
	v_mov_b32_e32 v93, v2
	v_mov_b32_e32 v94, v2
	v_mov_b32_e32 v95, v2
	v_mov_b32_e32 v96, v2
	v_mov_b32_e32 v97, v2
	v_mov_b32_e32 v98, v2
	v_mov_b32_e32 v99, v2
	v_mov_b32_e32 v104, v2
	v_mov_b32_e32 v105, v2
	v_mov_b32_e32 v106, v2
	v_mov_b32_e32 v107, v2
	v_mov_b32_e32 v108, v2
	v_mov_b32_e32 v109, v2
	v_mov_b32_e32 v110, v2
	v_mov_b32_e32 v111, v2
	v_mov_b32_e32 v76, v2
	v_mov_b32_e32 v77, v2
	v_mov_b32_e32 v78, v2
	v_mov_b32_e32 v79, v2
	v_mov_b32_e32 v84, v2
	v_mov_b32_e32 v85, v2
	v_mov_b32_e32 v86, v2
	v_mov_b32_e32 v87, v2
	v_mov_b32_e32 v100, v2
	v_mov_b32_e32 v101, v2
	v_mov_b32_e32 v102, v2
	v_mov_b32_e32 v103, v2
	v_mov_b32_e32 v112, v2
	v_mov_b32_e32 v113, v2
	v_mov_b32_e32 v114, v2
	v_mov_b32_e32 v115, v2
	v_mov_b32_e32 v116, v2
	v_mov_b32_e32 v117, v2
	v_mov_b32_e32 v118, v2
	v_mov_b32_e32 v119, v2
	v_mov_b32_e32 v120, v2
	v_mov_b32_e32 v121, v2
	v_mov_b32_e32 v122, v2
	v_mov_b32_e32 v123, v2
	v_mov_b32_e32 v124, v2
	v_mov_b32_e32 v125, v2
	v_mov_b32_e32 v126, v2
	v_mov_b32_e32 v127, v2
	v_mov_b32_e32 v128, v2
	v_mov_b32_e32 v129, v2
	v_mov_b32_e32 v130, v2
	v_mov_b32_e32 v131, v2
	s_mov_b64 s[56:57], 0x80
	.p2align 6
